# adds adaLN weight prefetch and final-norm row loop fast path (no store-ack serialisation) on top of v13
# speedup vs baseline: 1.0350x; 1.0094x over previous
; DI void phase_prep(char* smem) {
;     ...
;     for (int u = bid; u < 192; u += nb) {
;       const int l = u / 96, n = (u % 96) * 64 + lane, kg = wid;
;       const float* wp = mw + (size_t)l * 1024 * 6144 + n;
;       float acc[24];
; #pragma unroll
;       for (int s = 0; s < 24; ++s) acc[s] = 0.f;
;       for (int k = kg * 128; k < kg * 128 + 128; k += 4) {
;         const float w0 = wp[(size_t)k * 6144], w1 = wp[(size_t)(k + 1) * 6144], w2 = wp[(size_t)(k + 2) * 6144], w3 = wp[(size_t)(k + 3) * 6144];
; #pragma unroll
;         for (int s = 0; s < 24; ++s) {
;           const f32x4 c4 = *(const f32x4*)(scs + s * 1024 + k);
;           acc[s] += c4[0] * w0 + c4[1] * w1 + c4[2] * w2 + c4[3] * w3;
;         }
;       }
.LBB0_46:
	s_mul_hi_i32 s4, s29, 0x2aaaaaab
	s_lshr_b32 s5, s4, 31
	s_ashr_i32 s4, s4, 4
	s_add_i32 s24, s4, s5
	v_lshl_or_b32 v2, s29, 6, v1
	s_mul_i32 s26, s24, 0x1800
	v_subrev_u32_e32 v2, s26, v2
	v_ashrrev_i32_e32 v3, 31, v2
	v_lshlrev_b64 v[2:3], 2, v[2:3]
	v_mad_i64_i32 v[2:3], s[4:5], s24, v66, v[2:3]
	v_mov_b32_e32 v30, 0
	v_lshl_add_u64 v[32:33], v[28:29], 0, v[2:3]
	s_mov_b64 s[22:23], 0
	v_mov_b32_e32 v68, v65
	v_mov_b32_e32 v69, v64
	v_mov_b32_e32 v31, v30
	v_mov_b32_e32 v34, v30
	v_mov_b32_e32 v35, v30
	v_mov_b32_e32 v36, v30
	v_mov_b32_e32 v37, v30
	v_mov_b32_e32 v38, v30
	v_mov_b32_e32 v39, v30
	v_mov_b32_e32 v40, v30
	v_mov_b32_e32 v41, v30
	v_mov_b32_e32 v42, v30
	v_mov_b32_e32 v43, v30
	v_mov_b32_e32 v44, v30
	v_mov_b32_e32 v45, v30
	v_mov_b32_e32 v46, v30
	v_mov_b32_e32 v47, v30
	v_mov_b32_e32 v48, v30
	v_mov_b32_e32 v49, v30
	v_mov_b32_e32 v50, v30
	v_mov_b32_e32 v51, v30
	v_mov_b32_e32 v52, v30
	v_mov_b32_e32 v53, v30
	v_mov_b32_e32 v54, v30
	v_mov_b32_e32 v55, v30
	v_mov_b32_e32 v153, 0
	v_mov_b32_e32 v155, 0
	v_mov_b32_e32 v154, 0x6000
	v_mov_b32_e32 v156, 0x60000
	v_add_co_u32_e64 v150, s[4:5], s3, v32
	s_nop 1
	v_addc_co_u32_e64 v151, s[4:5], -1, v33, s[4:5]
	v_lshl_add_u64 v[150:151], v[150:151], 0, s[8:9]
	global_load_dword v146, v[150:151], off
	v_lshl_add_u64 v[150:151], v[150:151], 0, v[154:155]
	global_load_dword v147, v[150:151], off
	v_lshl_add_u64 v[150:151], v[150:151], 0, v[154:155]
	global_load_dword v148, v[150:151], off
	v_lshl_add_u64 v[150:151], v[150:151], 0, v[154:155]
	global_load_dword v149, v[150:151], off
	v_lshl_add_u64 v[150:151], v[150:151], 0, v[154:155]
	global_load_dword v146, v[150:151], off
	v_lshl_add_u64 v[150:151], v[150:151], 0, v[154:155]
	global_load_dword v147, v[150:151], off
	v_lshl_add_u64 v[150:151], v[150:151], 0, v[154:155]
	global_load_dword v148, v[150:151], off
	v_lshl_add_u64 v[150:151], v[150:151], 0, v[154:155]
	global_load_dword v149, v[150:151], off
	v_lshl_add_u64 v[150:151], v[150:151], 0, v[154:155]
	global_load_dword v146, v[150:151], off
	v_lshl_add_u64 v[150:151], v[150:151], 0, v[154:155]
	global_load_dword v147, v[150:151], off
	v_lshl_add_u64 v[150:151], v[150:151], 0, v[154:155]
	global_load_dword v148, v[150:151], off
	v_lshl_add_u64 v[150:151], v[150:151], 0, v[154:155]
	global_load_dword v149, v[150:151], off
	v_lshl_add_u64 v[150:151], v[150:151], 0, v[154:155]
.LBB0_47:
	v_add_co_u32_e64 v58, s[4:5], s3, v32
	global_load_dword v56, v[32:33], off
	s_nop 0
	v_addc_co_u32_e64 v59, s[4:5], -1, v33, s[4:5]
	v_add_co_u32_e64 v60, s[4:5], s14, v32
	ds_read_b128 v[14:17], v68
	ds_read_b128 v[2:5], v68 offset:4096
	ds_read_b128 v[18:21], v68 offset:8192
	ds_read_b128 v[6:9], v68 offset:12288
	ds_read_b128 v[22:25], v68 offset:16384
	ds_read_b128 v[10:13], v68 offset:20480
	ds_read_b128 v[86:89], v68 offset:24576
	ds_read_b128 v[90:93], v68 offset:28672
	v_addc_co_u32_e64 v61, s[4:5], -1, v33, s[4:5]
	v_add_co_u32_e64 v62, s[4:5], s15, v32
	v_add_u32_e32 v70, 0xffff0000, v68
	s_nop 0
	v_addc_co_u32_e64 v63, s[4:5], -1, v33, s[4:5]
	global_load_dword v138, v[58:59], off
	global_load_dword v140, v[60:61], off
	global_load_dword v142, v[62:63], off
	v_add_u32_e32 v150, 20, v69
	v_cmp_le_i32_e64 s[4:5], v150, v57
	s_nop 1
	v_cndmask_b32_e64 v152, 0, v156, s[4:5]
	v_lshl_add_u64 v[150:151], v[32:33], 0, v[152:153]
	global_load_dword v146, v[150:151], off
	v_lshl_add_u64 v[150:151], v[58:59], 0, v[152:153]
	global_load_dword v147, v[150:151], off
	v_lshl_add_u64 v[150:151], v[60:61], 0, v[152:153]
	global_load_dword v148, v[150:151], off
	v_lshl_add_u64 v[150:151], v[62:63], 0, v[152:153]
	global_load_dword v149, v[150:151], off
	v_add_u32_e32 v71, 0xffff1000, v68
	v_add_u32_e32 v72, 0xffff2000, v68
	v_add_u32_e32 v73, 0xffff3000, v68
	v_add_u32_e32 v74, 0xffff4000, v68
	v_add_u32_e32 v75, 0xffff5000, v68
	v_add_u32_e32 v76, 0xffff6000, v68
	v_add_u32_e32 v77, 0xffff7000, v68
	v_add_u32_e32 v78, 0xffff8000, v68
	v_add_u32_e32 v79, 0xffff9000, v68
	v_add_u32_e32 v80, 0xffffa000, v68
	v_add_u32_e32 v81, 0xffffb000, v68
	v_add_u32_e32 v82, 0xffffc000, v68
	v_add_u32_e32 v83, 0xffffd000, v68
	v_add_u32_e32 v84, 0xffffe000, v68
	v_add_u32_e32 v85, 0xfffff000, v68
	ds_read_b128 v[58:61], v70
	ds_read_b128 v[94:97], v71
	ds_read_b128 v[98:101], v72
	ds_read_b128 v[70:73], v73
	ds_read_b128 v[102:105], v74
	ds_read_b128 v[106:109], v75
	ds_read_b128 v[110:113], v76
	ds_read_b128 v[74:77], v77
	ds_read_b128 v[114:117], v78
	ds_read_b128 v[118:121], v79
	ds_read_b128 v[122:125], v80
	ds_read_b128 v[78:81], v81
	ds_read_b128 v[126:129], v82
	ds_read_b128 v[130:133], v83
	ds_read_b128 v[134:137], v84
	ds_read_b128 v[82:85], v85
	s_waitcnt lgkmcnt(14)
	v_mov_b32_e32 v63, v2
	v_mov_b32_e32 v2, v15
	v_mov_b32_e32 v15, v4
	v_mov_b32_e32 v4, v17
	v_mov_b32_e32 v17, v6
	v_mov_b32_e32 v6, v19
	v_mov_b32_e32 v19, v8
	v_mov_b32_e32 v8, v21
	v_mov_b32_e32 v21, v10
	v_mov_b32_e32 v10, v23
	v_mov_b32_e32 v23, v12
	v_mov_b32_e32 v12, v25
	v_mov_b32_e32 v25, v94
	v_mov_b32_e32 v94, v59
	v_mov_b32_e32 v59, v96
	v_mov_b32_e32 v96, v61
	s_waitcnt lgkmcnt(12)
	v_mov_b32_e32 v61, v70
	v_mov_b32_e32 v70, v99
	v_mov_b32_e32 v99, v72
	v_mov_b32_e32 v72, v101
	s_waitcnt lgkmcnt(10)
	v_mov_b32_e32 v101, v106
	v_mov_b32_e32 v106, v103
	v_mov_b32_e32 v103, v108
	v_mov_b32_e32 v108, v105
	s_waitcnt lgkmcnt(8)
	v_mov_b32_e32 v105, v74
	v_mov_b32_e32 v74, v111
	v_mov_b32_e32 v111, v76
	v_mov_b32_e32 v76, v113
	s_waitcnt lgkmcnt(6)
	v_mov_b32_e32 v113, v118
	v_mov_b32_e32 v118, v115
	v_mov_b32_e32 v115, v120
	v_mov_b32_e32 v120, v117
	s_waitcnt lgkmcnt(4)
; DI void phase_prep(char* smem) {
;     ...
;       for (int k = kg * 128; k < kg * 128 + 128; k += 4) {
;         const float w0 = wp[(size_t)k * 6144], w1 = wp[(size_t)(k + 1) * 6144], w2 = wp[(size_t)(k + 2) * 6144], w3 = wp[(size_t)(k + 3) * 6144];
; #pragma unroll
;         for (int s = 0; s < 24; ++s) {
;           const f32x4 c4 = *(const f32x4*)(scs + s * 1024 + k);
;           acc[s] += c4[0] * w0 + c4[1] * w1 + c4[2] * w2 + c4[3] * w3;
;         }
;       }
; #pragma unroll
;       for (int s = 0; s < 24; ++s) red[(kg * 24 + s) * 64 + lane] = acc[s];
;       __syncthreads();
;       for (int o = tid; o < 24 * 64; o += 512) {
;         const int s = o >> 6, c = o & 63;
;         float sum = 0.f;
; #pragma unroll
;         for (int g = 0; g < 8; ++g) sum += red[(g * 24 + s) * 64 + c];
	v_mov_b32_e32 v117, v78
	v_mov_b32_e32 v78, v123
	v_mov_b32_e32 v123, v80
	v_mov_b32_e32 v80, v125
	s_waitcnt lgkmcnt(2)
	v_mov_b32_e32 v125, v130
	v_mov_b32_e32 v130, v127
	v_mov_b32_e32 v127, v132
	v_mov_b32_e32 v132, v129
	s_waitcnt lgkmcnt(0)
	v_mov_b32_e32 v129, v82
	v_mov_b32_e32 v82, v135
	v_mov_b32_e32 v62, v14
	v_mov_b32_e32 v14, v16
	v_mov_b32_e32 v16, v18
	v_mov_b32_e32 v18, v20
	v_mov_b32_e32 v20, v22
	v_mov_b32_e32 v22, v24
	v_mov_b32_e32 v24, v58
	v_mov_b32_e32 v58, v60
	v_mov_b32_e32 v60, v98
	v_mov_b32_e32 v98, v100
	v_mov_b32_e32 v100, v102
	v_mov_b32_e32 v102, v104
	v_mov_b32_e32 v104, v110
	v_mov_b32_e32 v110, v112
	v_mov_b32_e32 v112, v114
	v_mov_b32_e32 v114, v116
	v_mov_b32_e32 v116, v122
	v_mov_b32_e32 v122, v124
	v_mov_b32_e32 v124, v126
	v_mov_b32_e32 v126, v128
	v_mov_b32_e32 v128, v134
	s_waitcnt vmcnt(5)
	v_pk_mul_f32 v[94:95], v[140:141], v[94:95] op_sel_hi:[0,1]
	v_pk_mul_f32 v[70:71], v[140:141], v[70:71] op_sel_hi:[0,1]
	v_pk_mul_f32 v[106:107], v[140:141], v[106:107] op_sel_hi:[0,1]
	v_pk_mul_f32 v[74:75], v[140:141], v[74:75] op_sel_hi:[0,1]
	v_pk_mul_f32 v[118:119], v[140:141], v[118:119] op_sel_hi:[0,1]
	v_pk_mul_f32 v[78:79], v[140:141], v[78:79] op_sel_hi:[0,1]
	v_pk_mul_f32 v[130:131], v[140:141], v[130:131] op_sel_hi:[0,1]
	v_pk_mul_f32 v[82:83], v[140:141], v[82:83] op_sel_hi:[0,1]
	v_pk_mul_f32 v[2:3], v[140:141], v[2:3] op_sel_hi:[0,1]
	v_pk_mul_f32 v[6:7], v[140:141], v[6:7] op_sel_hi:[0,1]
	v_pk_mul_f32 v[10:11], v[140:141], v[10:11] op_sel_hi:[0,1]
	v_mov_b32_e32 v134, v136
	v_mov_b32_e32 v135, v84
	v_pk_fma_f32 v[24:25], v[138:139], v[24:25], v[94:95] op_sel_hi:[0,1,1]
	v_pk_fma_f32 v[60:61], v[138:139], v[60:61], v[70:71] op_sel_hi:[0,1,1]
	v_pk_fma_f32 v[70:71], v[138:139], v[100:101], v[106:107] op_sel_hi:[0,1,1]
	v_pk_fma_f32 v[74:75], v[138:139], v[104:105], v[74:75] op_sel_hi:[0,1,1]
	v_pk_fma_f32 v[94:95], v[138:139], v[112:113], v[118:119] op_sel_hi:[0,1,1]
	v_pk_fma_f32 v[78:79], v[138:139], v[116:117], v[78:79] op_sel_hi:[0,1,1]
	v_pk_fma_f32 v[100:101], v[138:139], v[124:125], v[130:131] op_sel_hi:[0,1,1]
	v_pk_fma_f32 v[82:83], v[138:139], v[128:129], v[82:83] op_sel_hi:[0,1,1]
	v_pk_fma_f32 v[2:3], v[138:139], v[62:63], v[2:3] op_sel_hi:[0,1,1]
	v_pk_fma_f32 v[6:7], v[138:139], v[16:17], v[6:7] op_sel_hi:[0,1,1]
	v_pk_fma_f32 v[10:11], v[138:139], v[20:21], v[10:11] op_sel_hi:[0,1,1]
	v_mov_b32_e32 v139, v140
	s_waitcnt vmcnt(4)
	v_pk_fma_f32 v[16:17], v[142:143], v[58:59], v[24:25] op_sel_hi:[0,1,1]
	v_pk_fma_f32 v[20:21], v[142:143], v[98:99], v[60:61] op_sel_hi:[0,1,1]
	v_pk_fma_f32 v[24:25], v[142:143], v[102:103], v[70:71] op_sel_hi:[0,1,1]
	v_pk_fma_f32 v[58:59], v[142:143], v[110:111], v[74:75] op_sel_hi:[0,1,1]
	v_pk_fma_f32 v[60:61], v[142:143], v[114:115], v[94:95] op_sel_hi:[0,1,1]
	v_pk_fma_f32 v[62:63], v[142:143], v[122:123], v[78:79] op_sel_hi:[0,1,1]
	v_pk_fma_f32 v[70:71], v[142:143], v[126:127], v[100:101] op_sel_hi:[0,1,1]
	v_pk_fma_f32 v[74:75], v[142:143], v[134:135], v[82:83] op_sel_hi:[0,1,1]
	v_pk_fma_f32 v[2:3], v[142:143], v[14:15], v[2:3] op_sel_hi:[0,1,1]
	v_pk_fma_f32 v[6:7], v[142:143], v[18:19], v[6:7] op_sel_hi:[0,1,1]
	v_pk_fma_f32 v[10:11], v[142:143], v[22:23], v[10:11] op_sel_hi:[0,1,1]
	v_pk_mul_f32 v[14:15], v[138:139], v[90:91]
	v_mov_b32_e32 v143, v56
	v_mul_f32_e32 v86, v138, v86
	v_mul_f32_e32 v144, v140, v87
	v_pk_fma_f32 v[2:3], v[56:57], v[4:5], v[2:3] op_sel_hi:[0,1,1]
	v_pk_fma_f32 v[4:5], v[56:57], v[8:9], v[6:7] op_sel_hi:[0,1,1]
	v_pk_mul_f32 v[8:9], v[142:143], v[92:93]
	v_mov_b32_e32 v87, v14
	v_mov_b32_e32 v145, v15
	v_mul_f32_e32 v136, v56, v89
	v_mul_f32_e32 v88, v142, v88
	v_pk_add_f32 v[50:51], v[50:51], v[2:3]
	v_pk_add_f32 v[2:3], v[86:87], v[144:145]
	v_mov_b32_e32 v89, v8
	v_add_u32_e32 v69, 4, v69
	v_mov_b32_e32 v84, v137
	v_mov_b32_e32 v137, v9
	v_pk_add_f32 v[2:3], v[88:89], v[2:3]
	v_cmp_ge_i32_e64 s[4:5], v69, v57
	v_pk_fma_f32 v[16:17], v[56:57], v[96:97], v[16:17] op_sel_hi:[0,1,1]
	v_pk_fma_f32 v[18:19], v[56:57], v[72:73], v[20:21] op_sel_hi:[0,1,1]
	v_pk_fma_f32 v[20:21], v[56:57], v[108:109], v[24:25] op_sel_hi:[0,1,1]
	v_pk_fma_f32 v[22:23], v[56:57], v[76:77], v[58:59] op_sel_hi:[0,1,1]
	v_pk_fma_f32 v[24:25], v[56:57], v[120:121], v[60:61] op_sel_hi:[0,1,1]
	v_pk_fma_f32 v[58:59], v[56:57], v[80:81], v[62:63] op_sel_hi:[0,1,1]
	v_pk_fma_f32 v[60:61], v[56:57], v[132:133], v[70:71] op_sel_hi:[0,1,1]
	v_pk_fma_f32 v[62:63], v[56:57], v[84:85], v[74:75] op_sel_hi:[0,1,1]
	v_pk_fma_f32 v[6:7], v[56:57], v[12:13], v[10:11] op_sel_hi:[0,1,1]
	v_pk_add_f32 v[2:3], v[136:137], v[2:3]
	v_add_u32_e32 v68, 16, v68
	v_lshl_add_u64 v[32:33], v[32:33], 0, s[8:9]
	s_or_b64 s[22:23], s[4:5], s[22:23]
	v_pk_add_f32 v[34:35], v[34:35], v[16:17]
	v_pk_add_f32 v[36:37], v[36:37], v[18:19]
	v_pk_add_f32 v[38:39], v[38:39], v[20:21]
	v_pk_add_f32 v[40:41], v[40:41], v[22:23]
	v_pk_add_f32 v[42:43], v[42:43], v[24:25]
	v_pk_add_f32 v[44:45], v[44:45], v[58:59]
	v_pk_add_f32 v[46:47], v[46:47], v[60:61]
	v_pk_add_f32 v[48:49], v[48:49], v[62:63]
	v_pk_add_f32 v[52:53], v[52:53], v[4:5]
	v_pk_add_f32 v[54:55], v[54:55], v[6:7]
	v_pk_add_f32 v[30:31], v[30:31], v[2:3]
	s_andn2_b64 exec, exec, s[22:23]
	s_cbranch_execnz .LBB0_47
	s_waitcnt vmcnt(0)
	s_or_b64 exec, exec, s[22:23]
	ds_write2st64_b32 v67, v34, v35 offset1:1
	ds_write2st64_b32 v67, v36, v37 offset0:2 offset1:3
	ds_write2st64_b32 v67, v38, v39 offset0:4 offset1:5
	ds_write2st64_b32 v67, v40, v41 offset0:6 offset1:7
	ds_write2st64_b32 v67, v42, v43 offset0:8 offset1:9
	ds_write2st64_b32 v67, v44, v45 offset0:10 offset1:11
	ds_write2st64_b32 v67, v46, v47 offset0:12 offset1:13
	ds_write2st64_b32 v67, v48, v49 offset0:14 offset1:15
	ds_write2st64_b32 v67, v50, v51 offset0:16 offset1:17
	ds_write2st64_b32 v67, v52, v53 offset0:18 offset1:19
	ds_write2st64_b32 v67, v54, v55 offset0:20 offset1:21
	ds_write2st64_b32 v67, v30, v31 offset0:22 offset1:23
	s_waitcnt lgkmcnt(0)
	s_barrier
	s_and_saveexec_b64 s[22:23], vcc
	s_cbranch_execz .LBB0_45
	s_mul_i32 s4, s24, 0x60
	s_sub_i32 s4, s29, s4
	v_lshl_or_b32 v4, s4, 6, v1
	v_add_u32_e32 v2, s26, v4
	v_ashrrev_i32_e32 v5, 31, v4
	v_ashrrev_i32_e32 v3, 31, v2
	s_mul_hi_i32 s25, s24, 24
	s_mul_i32 s24, s24, 24
	v_lshl_add_u64 v[2:3], v[2:3], 2, s[10:11]
	v_lshl_add_u64 v[4:5], v[4:5], 2, s[6:7]
	s_mov_b64 s[26:27], 0
	v_mov_b32_e32 v6, v26

; DI int otid() { int t = threadIdx.x; asm volatile("" : "+v"(t)); return t; }
; DI int obid() { int b = blockIdx.x; asm volatile("" : "+s"(b)); return b; }
; #define ROW_LOOP(row, NROWS, BID, NB, WID) \
;   for (int it_ = 0, row = ((NB) == 256 ? ((((BID) & 7)) << 8) + (((BID) >> 3) << 3) + (WID) : (BID) * 8 + (WID)); row < (NROWS); \
;        ++it_, row = ((NB) == 256 ? ((((BID) & 7) + 8 * it_) << 8) + (((BID) >> 3) << 3) + (WID) : (BID) * 8 + (WID) + it_ * (NB) * 8))
; DI KParams kp() { KParams k = (KParams)__builtin_amdgcn_kernarg_segment_ptr(); asm volatile("" : "+s"(k)); return k; }
; DI void phase_final() {
;   KParams P = kp();
;   const int nb = gridDim.x, bid = obid(), lane = otid() & 63, wid = otid() >> 6;
;   char* ws = P->ws;
;   float* out = P->out; const float* fg = P->final_g; const u16* xb = WSP(u16, OFF_XB);
;   ROW_LOOP(row, NSEQ * SEQL, bid, nb, wid) {
;     f32x4* xr = (f32x4*)(out + (size_t)row * 1024);
;     const u32x2* xi = (const u32x2*)(xb + (size_t)row * 1024);
;     f32x4 v[4]; float ss = 0.f;
; #pragma unroll
;     for (int i = 0; i < 4; ++i) { const u32x2 w = xi[lane + 64 * i]; v[i] = f32x4{__uint_as_float(w[0] << 16), __uint_as_float(w[0] & 0xffff0000u), __uint_as_float(w[1] << 16), __uint_as_float(w[1] & 0xffff0000u)};
;       ss += v[i][0] * v[i][0] + v[i][1] * v[i][1] + v[i][2] * v[i][2] + v[i][3] * v[i][3]; }
;     ss = wsum(ss);
;     const float rstd = rsqrtf(ss * (1.f / 1024.f) + EPS);
; #pragma unroll
;     for (int i = 0; i < 4; ++i) {
;       const f32x4 g = *(const f32x4*)(fg + (lane + 64 * i) * 4);
;       f32x4 o; o[0] = v[i][0] * rstd * g[0]; o[1] = v[i][1] * rstd * g[1]; o[2] = v[i][2] * rstd * g[2]; o[3] = v[i][3] * rstd * g[3];
;       xr[lane + 64 * i] = o;
;     }
;   }
; }
.LBB0_1647:
	v_ashrrev_i32_e32 v14, 6, v182
	v_add_u32_e32 v10, s0, v14
	s_mov_b32 s0, 0x18000
	v_cmp_gt_i32_e32 vcc, s0, v10
	s_and_saveexec_b64 s[0:1], vcc
	s_cbranch_execz .LBB0_1652
	v_and_b32_e32 v8, 63, v0
	v_and_b32_e32 v0, 64, v183
	v_add_u32_e32 v0, 64, v0
	v_xor_b32_e32 v1, 32, v183
	v_cmp_lt_i32_e32 vcc, v1, v0
	s_load_dwordx4 s[8:11], s[96:97], 0x88
	s_load_dwordx2 s[0:1], s[96:97], 0x98
	v_cndmask_b32_e32 v1, v183, v1, vcc
	v_lshlrev_b32_e32 v15, 2, v1
	v_xor_b32_e32 v1, 16, v183
	v_cmp_lt_i32_e32 vcc, v1, v0
	v_mov_b32_e32 v13, 0
	s_lshl_b32 s3, s80, 8
	v_cndmask_b32_e32 v1, v183, v1, vcc
	v_lshlrev_b32_e32 v16, 2, v1
	v_xor_b32_e32 v1, 8, v183
	v_cmp_lt_i32_e32 vcc, v1, v0
	v_lshlrev_b32_e32 v12, 4, v8
	v_lshlrev_b32_e32 v8, 3, v8
	v_cndmask_b32_e32 v1, v183, v1, vcc
	v_lshlrev_b32_e32 v17, 2, v1
	v_xor_b32_e32 v1, 4, v183
	v_cmp_lt_i32_e32 vcc, v1, v0
	v_mov_b32_e32 v9, v13
	s_and_b32 s3, s3, 0x700
	v_cndmask_b32_e32 v1, v183, v1, vcc
	v_lshlrev_b32_e32 v18, 2, v1
	v_xor_b32_e32 v1, 2, v183
	v_cmp_lt_i32_e32 vcc, v1, v0
	s_and_b32 s6, s80, -8
	s_waitcnt lgkmcnt(0)
	v_lshl_add_u64 v[8:9], s[0:1], 0, v[8:9]
	v_cndmask_b32_e32 v1, v183, v1, vcc
	v_lshlrev_b32_e32 v19, 2, v1
	v_xor_b32_e32 v1, 1, v183
	v_cmp_lt_i32_e32 vcc, v1, v0
	s_mov_b64 s[0:1], 0x2b630100
	v_or_b32_e32 v2, 0x400, v12
	v_cndmask_b32_e32 v0, v183, v1, vcc
	v_mov_b32_e32 v3, v13
	v_or_b32_e32 v4, 0x800, v12
	v_mov_b32_e32 v5, v13
	v_or_b32_e32 v6, 0xc00, v12
	v_mov_b32_e32 v7, v13
	v_lshl_add_u64 v[8:9], v[8:9], 0, s[0:1]
	s_add_i32 s0, s3, s6
	s_mov_b32 s2, 0
	v_lshlrev_b32_e32 v20, 2, v0
	v_lshl_add_u64 v[0:1], s[8:9], 0, v[12:13]
	v_lshl_add_u64 v[2:3], s[8:9], 0, v[2:3]
	v_lshl_add_u64 v[4:5], s[8:9], 0, v[4:5]
	v_lshl_add_u64 v[6:7], s[8:9], 0, v[6:7]
	v_lshl_add_u64 v[12:13], s[10:11], 0, v[12:13]
	s_add_i32 s3, s0, 0x800
	s_mov_b64 s[0:1], 0
	v_mov_b32_e32 v21, 0x358637bd
	s_mov_b32 s6, 0x800000
	s_mov_b32 s7, 0x17fff
	s_and_b64 vcc, exec, s[4:5]
	s_cbranch_vccz .LBB0_1650
	v_readfirstlane_b32 s3, v10
	s_mov_b32 s1, 0
	global_load_dwordx4 v[64:67], v[0:1], off
	global_load_dwordx4 v[68:71], v[2:3], off
	global_load_dwordx4 v[72:75], v[4:5], off
	global_load_dwordx4 v[76:79], v[6:7], off
	s_nop 3
	s_lshl_b32 s0, s3, 11
	v_lshl_add_u64 v[120:121], v[8:9], 0, s[0:1]
	global_load_dwordx2 v[80:81], v[120:121], off
	global_load_dwordx2 v[82:83], v[120:121], off offset:512
	global_load_dwordx2 v[84:85], v[120:121], off offset:1024
	global_load_dwordx2 v[86:87], v[120:121], off offset:1536
	s_waitcnt vmcnt(0)
	s_branch .Lff_body
.Lff_top:
	s_waitcnt vmcnt(4)
.Lff_body:
	v_lshlrev_b32_e32 v90, 16, v80
	v_and_b32_e32 v88, 0xffff0000, v80
	v_lshlrev_b32_e32 v92, 16, v81
	v_and_b32_e32 v94, 0xffff0000, v81
	v_lshlrev_b32_e32 v91, 16, v82
	v_and_b32_e32 v89, 0xffff0000, v82
	v_lshlrev_b32_e32 v93, 16, v83
	v_and_b32_e32 v95, 0xffff0000, v83
	v_lshlrev_b32_e32 v98, 16, v84
	v_and_b32_e32 v96, 0xffff0000, v84
	v_lshlrev_b32_e32 v100, 16, v85
	v_and_b32_e32 v102, 0xffff0000, v85
	v_lshlrev_b32_e32 v99, 16, v86
	v_and_b32_e32 v97, 0xffff0000, v86
	v_lshlrev_b32_e32 v101, 16, v87
	v_and_b32_e32 v103, 0xffff0000, v87
	s_add_i32 s2, s3, 0x800
	s_cmp_lt_i32 s2, 0x18000
	s_cselect_b32 s0, s2, s3
	s_lshl_b32 s0, s0, 11
	v_lshl_add_u64 v[120:121], v[8:9], 0, s[0:1]
	global_load_dwordx2 v[80:81], v[120:121], off
	global_load_dwordx2 v[82:83], v[120:121], off offset:512
	global_load_dwordx2 v[84:85], v[120:121], off offset:1024
	global_load_dwordx2 v[86:87], v[120:121], off offset:1536
	v_pk_mul_f32 v[112:113], v[88:89], v[88:89]
	v_pk_fma_f32 v[112:113], v[90:91], v[90:91], v[112:113]
	v_pk_fma_f32 v[112:113], v[92:93], v[92:93], v[112:113]
	v_pk_fma_f32 v[112:113], v[94:95], v[94:95], v[112:113]
	v_pk_mul_f32 v[114:115], v[96:97], v[96:97]
	v_pk_fma_f32 v[114:115], v[98:99], v[98:99], v[114:115]
	v_pk_fma_f32 v[114:115], v[100:101], v[100:101], v[114:115]
	v_pk_fma_f32 v[114:115], v[102:103], v[102:103], v[114:115]
	v_add_f32_e32 v117, v112, v113
	v_add_f32_e32 v117, v117, v114
	v_add_f32_e32 v117, v117, v115
	s_lshl_b32 s0, s3, 12
	ds_bpermute_b32 v116, v15, v117
	v_lshl_add_u64 v[122:123], v[12:13], 0, s[0:1]
	s_waitcnt lgkmcnt(0)
	v_add_f32_e32 v116, v117, v116
	ds_bpermute_b32 v117, v16, v116
	s_waitcnt lgkmcnt(0)
	v_add_f32_e32 v116, v116, v117
	ds_bpermute_b32 v117, v17, v116
	s_waitcnt lgkmcnt(0)
	v_add_f32_e32 v116, v116, v117
	ds_bpermute_b32 v117, v18, v116
	s_waitcnt lgkmcnt(0)
	v_add_f32_e32 v116, v116, v117
	ds_bpermute_b32 v117, v19, v116
	s_waitcnt lgkmcnt(0)
	v_add_f32_e32 v116, v116, v117
	ds_bpermute_b32 v117, v20, v116
	s_waitcnt lgkmcnt(0)
	v_add_f32_e32 v116, v116, v117
	v_fmamk_f32 v116, v116, 0x3a800000, v21
	v_mul_f32_e32 v117, 0x4b800000, v116
	v_cmp_gt_f32_e32 vcc, 0x800000, v116
	s_nop 1
	v_cndmask_b32_e32 v116, v116, v117, vcc
	v_rsq_f32_e32 v116, v116
	s_nop 0
	v_mul_f32_e32 v117, 0x45800000, v116
	v_cndmask_b32_e32 v118, v116, v117, vcc
	v_mul_f32_e32 v104, v118, v90
	v_mul_f32_e32 v105, v118, v88
	v_mul_f32_e32 v106, v118, v92
	v_mul_f32_e32 v107, v118, v94
	v_mul_f32_e32 v104, v64, v104
	v_mul_f32_e32 v105, v65, v105
	v_mul_f32_e32 v106, v66, v106
	v_mul_f32_e32 v107, v67, v107
	global_store_dwordx4 v[122:123], v[104:107], off
	v_mul_f32_e32 v108, v118, v91
	v_mul_f32_e32 v109, v118, v89
	v_mul_f32_e32 v110, v118, v93
	v_mul_f32_e32 v111, v118, v95
	v_mul_f32_e32 v108, v68, v108
	v_mul_f32_e32 v109, v69, v109
	v_mul_f32_e32 v110, v70, v110
	v_mul_f32_e32 v111, v71, v111
	global_store_dwordx4 v[122:123], v[108:111], off offset:1024
	v_mul_f32_e32 v104, v118, v98
	v_mul_f32_e32 v105, v118, v96
	v_mul_f32_e32 v106, v118, v100
	v_mul_f32_e32 v107, v118, v102
	v_mul_f32_e32 v104, v72, v104
	v_mul_f32_e32 v105, v73, v105
	v_mul_f32_e32 v106, v74, v106
	v_mul_f32_e32 v107, v75, v107
	global_store_dwordx4 v[122:123], v[104:107], off offset:2048
	v_mul_f32_e32 v108, v118, v99
	v_mul_f32_e32 v109, v118, v97
	v_mul_f32_e32 v110, v118, v101
	v_mul_f32_e32 v111, v118, v103
	v_mul_f32_e32 v108, v76, v108
	v_mul_f32_e32 v109, v77, v109
	v_mul_f32_e32 v110, v78, v110
	v_mul_f32_e32 v111, v79, v111
	global_store_dwordx4 v[122:123], v[108:111], off offset:3072
	s_mov_b32 s3, s2
	s_cmp_lt_i32 s2, 0x18000
	s_cbranch_scc1 .Lff_top
	s_branch .LBB0_1652
